# grid barrier: XCD-local release (no L2 write-back, no cross-XCD hop) after phases consumed on the producer's own XCD, guarded by a run-time placement check
# speedup vs baseline: 1.0089x; 1.0057x over previous
; #define LAS __attribute__((address_space(3)))
; __device__ __forceinline__ unsigned xb_add(unsigned* p, unsigned v) { return __hip_atomic_fetch_add(p, v, __ATOMIC_RELAXED, __HIP_MEMORY_SCOPE_AGENT); }
; __device__ __forceinline__ unsigned xb_xcc_id() { return (unsigned)__builtin_amdgcn_s_getreg((3 << 11) | 20) & 0xFu; }
; __device__ __forceinline__ XcdBarrier xcd_barrier_post(unsigned* bar, volatile LAS unsigned* st) {
;     XcdBarrier b; b.bar = bar; b.x = xb_xcc_id(); b.st = st;
;     if (threadIdx.x == 0) (void)xb_add(&bar[XB_XCNT(b.x)], 1u);
;     return b;
; }
; __global__ void __launch_bounds__(NTHR, 2) hymba_fwd(KArgs a) {
;     ...
;     (void)xcd_barrier_post((unsigned*)(ws0 + WS_BAR), (volatile LAS unsigned*)(lds + MISC_OFF) + 8);
.LBB0_644:
	s_or_b64 exec, exec, s[0:1]
	s_add_u32 s0, s78, 0x1e741000
	s_addc_u32 s1, s79, 0
	v_writelane_b32 v253, s0, 2
	s_barrier
	s_nop 0
	v_writelane_b32 v253, s1, 3
	s_getreg_b32 s4, hwreg(HW_REG_XCC_ID, 0, 4)
	s_mov_b32 s81, 0
	v_writelane_b32 v255, s81, 61
	v_cmp_eq_u32_e64 s[2:3], 0, v66
	s_mov_b64 s[0:1], exec
	s_nop 0
	v_writelane_b32 v253, s2, 4
	s_nop 1
	v_writelane_b32 v253, s3, 5
	s_and_b64 s[2:3], s[0:1], s[2:3]
	s_mov_b64 exec, s[2:3]
	s_cbranch_execz .LBB0_647
	s_mov_b64 s[2:3], exec
	v_mbcnt_lo_u32_b32 v0, s2, 0
	v_mbcnt_hi_u32_b32 v0, s3, v0
	v_cmp_eq_u32_e32 vcc, 0, v0
	s_and_b64 s[6:7], exec, vcc
	s_mov_b64 exec, s[6:7]
	s_cbranch_execz .LBB0_647
	s_lshl_b32 s4, s4, 8
	s_bcnt1_i32_b64 s2, s[2:3]
	s_and_b32 s4, s4, 0xf00
	v_mov_b32_e32 v1, s2
	v_readlane_b32 s2, v253, 2
	v_mov_b32_e32 v0, s4
	v_readlane_b32 s3, v253, 3
	s_nop 4
	global_atomic_add v0, v1, s[2:3] offset:1024
	v_readlane_b32 s5, v253, 0
	s_lshr_b32 s4, s4, 8
	s_and_b32 s5, s5, 7
	s_cmp_eq_u32 s4, s5
	s_cbranch_scc1 .Lxl_ok
	v_mov_b32_e32 v0, 1
	v_mov_b32_e32 v1, 0x220
	global_atomic_add v1, v0, s[2:3]
.Lxl_ok:
.LBB0_647:
	s_or_b64 exec, exec, s[0:1]
	s_lshr_b32 s5, s57, 6
	s_bfe_u32 s0, s57, 0x30006
	s_lshl_b32 s58, s0, 3
	s_lshl_b32 s89, s0, 10
	s_mul_hi_u32 s0, s5, 0x15555556
	s_lshr_b32 s1, s57, 2
	s_mul_i32 s0, s0, 12
	s_bfe_u32 s3, s57, 0x20006
	s_and_b32 s59, s1, 48
	s_lshr_b32 s1, s57, 3
	s_lshl_b32 s95, s5, 10
	s_sub_i32 s2, s5, s0
	s_or_b32 s4, s3, 8
	s_lshl_b32 s92, s3, 10
	s_and_b32 s6, s57, 0xffffffc0
	s_lshl_b32 s55, s5, 5
	s_and_b32 s60, s1, 0x1fffffe0
	s_add_i32 s61, s89, 0
	s_add_i32 s33, s95, 0
	s_lshl_b32 s0, s2, 3
	s_lshl_b32 s1, s4, 3
	s_lshl_b32 s62, s3, 12
	s_lshl_b32 s63, s2, 10
	s_lshl_b32 s75, s4, 10
	s_lshl_b32 s64, s3, 3
	s_add_i32 s93, s92, 0
	s_cmpk_lt_u32 s57, 0x100
	s_cselect_b64 s[66:67], -1, 0
	s_add_i32 s2, s33, 0x21400
	v_writelane_b32 v253, s2, 6
	s_mul_i32 s2, s5, 0x2080
	s_add_i32 s2, s2, 0
	s_add_i32 s2, s2, 0x11000
	v_writelane_b32 v253, s2, 7
	s_lshl_b32 s2, s72, 7
	v_writelane_b32 v253, s2, 8
	s_lshr_b32 s2, s57, 8
	s_lshl_b32 s7, s2, 6
	s_and_b32 s4, s55, 0x60
	v_writelane_b32 v253, s7, 9
	s_lshl_b32 s7, s2, 13
	s_lshl_b32 s74, s3, 5
	s_cmp_eq_u32 s2, 1
	v_writelane_b32 v253, s7, 10
	s_cselect_b64 s[8:9], -1, 0
	v_writelane_b32 v253, s8, 11
	s_cmp_gt_u32 s3, 1
	s_cselect_b64 s[86:87], -1, 0
	v_writelane_b32 v253, s9, 12
	s_ashr_i32 s88, s72, 31
	s_lshl_b32 s2, s4, 7
	v_writelane_b32 v253, s4, 13
	s_cmpk_gt_i32 s72, 0x60
	v_writelane_b32 v253, s2, 14
	s_cselect_b32 s3, 48, 0
	s_lshl_b32 s2, s5, 14
	s_add_i32 s2, s2, 0
	v_writelane_b32 v253, s2, 15
	s_sub_i32 s2, s72, s3
	s_and_b32 s71, s3, 32
	s_sub_i32 s2, s2, s71
	s_lshl_b32 s71, s2, 3
	s_add_u32 s2, s78, 0x1e741200
	v_writelane_b32 v253, s3, 16
	s_addc_u32 s3, s79, 0
	v_writelane_b32 v253, s2, 17
	s_movk_i32 s85, 0x60
	s_movk_i32 s65, 0x1400
	v_writelane_b32 v253, s3, 18
	s_add_u32 s2, s78, 0x1e741400
	s_addc_u32 s3, s79, 0
	v_writelane_b32 v253, s2, 19
	v_mov_b32_e32 v215, 0
	v_mov_b32_e32 v244, 0x358637bd
	v_writelane_b32 v253, s3, 20
	s_add_u32 s2, s78, 0x1e741500
	s_addc_u32 s3, s79, 0
	v_writelane_b32 v253, s2, 21
	v_mov_b32_e32 v245, 0x260
	v_mov_b32_e32 v247, 1
	v_writelane_b32 v253, s3, 22
	s_add_u32 s2, s78, 0x1e741600
	s_addc_u32 s3, s79, 0
	v_writelane_b32 v253, s2, 23
	v_mov_b32_e32 v249, 0xff800000
	v_mov_b32_e32 v248, 0x461c4000
	v_writelane_b32 v253, s3, 24
	s_add_u32 s2, s78, 0x1e741700
	s_addc_u32 s3, s79, 0
	v_writelane_b32 v253, s2, 25
	v_mov_b32_e32 v252, 0x90
	s_mov_b32 s96, 0xff800000
	v_writelane_b32 v253, s3, 26
	s_add_u32 s2, s78, 0x1e741800
	s_addc_u32 s3, s79, 0
	v_writelane_b32 v253, s2, 27
	s_mov_b32 s97, 0x41000000
	s_movk_i32 s94, 0x200
	v_writelane_b32 v253, s3, 28
	s_add_u32 s2, s78, 0x1e741900
	s_addc_u32 s3, s79, 0
	v_writelane_b32 v253, s2, 29
	s_movk_i32 s84, 0x90
	s_movk_i32 s70, 0x2c00
	v_writelane_b32 v253, s3, 30
	s_add_u32 s2, s78, 0x1e741a00
	s_addc_u32 s3, s79, 0
	v_writelane_b32 v253, s2, 31
	s_mov_b64 s[90:91], 0x580
	s_nop 0
	v_writelane_b32 v253, s3, 32
	s_add_u32 s2, s78, 0x1e741b00
	s_addc_u32 s3, s79, 0
	v_writelane_b32 v253, s2, 33
	s_nop 1
	v_writelane_b32 v253, s3, 34
	s_add_u32 s2, s78, 0x1e741c00
	s_addc_u32 s3, s79, 0
; __device__ __forceinline__ int opaque_bid() { int b = blockIdx.x; asm volatile("" : "+s"(b)); return b; }
; #define GAS __attribute__((address_space(1)))
; __global__ void __launch_bounds__(NTHR, 2) hymba_fwd(KArgs a) {
;     ...
; #pragma nounroll
;     for (int it = 0; it < 28; ++it) {
;         GAS unsigned char* wsg_; asm volatile("s_mov_b64 %0, %1" : "=s"(wsg_) : "s"(ws0)); unsigned char* ws = (unsigned char*)wsg_;
;         const int wave = wave0, bid = opaque_bid();
;     ...
;         const int gw = bid * 8 + wave;
;         const int l = it / 14, s = it % 14;
;         int gid0 = 0, ng = 0, f = 0;
;         bf16_t* hn = (bf16_t*)(ws + WS_HN);
;         bf16_t* P = (bf16_t*)(ws + WS_ACT);
	v_writelane_b32 v253, s2, 35
	s_nop 1
	v_writelane_b32 v253, s3, 36
	s_add_u32 s2, s78, 0x1e741d00
	s_addc_u32 s3, s79, 0
	v_writelane_b32 v253, s2, 37
	s_nop 1
	v_writelane_b32 v253, s3, 38
	s_add_u32 s2, s78, 0x1e741e00
	s_addc_u32 s3, s79, 0
	v_writelane_b32 v253, s2, 39
	s_nop 1
	v_writelane_b32 v253, s3, 40
	s_add_u32 s2, s78, 0x1e741f00
	s_addc_u32 s3, s79, 0
	v_writelane_b32 v253, s2, 41
	s_nop 1
	v_writelane_b32 v253, s3, 42
	s_add_u32 s2, s78, 0x1e742000
	s_addc_u32 s3, s79, 0
	v_writelane_b32 v253, s2, 43
	s_nop 1
	v_writelane_b32 v253, s3, 44
	s_add_u32 s2, s78, 0x1e742100
	s_addc_u32 s3, s79, 0
	v_writelane_b32 v253, s2, 45
	s_nop 1
	v_writelane_b32 v253, s3, 46
	s_add_u32 s2, s78, 0x1e742200
	s_addc_u32 s3, s79, 0
	v_writelane_b32 v253, s2, 47
	s_nop 1
	v_writelane_b32 v253, s3, 48
	s_add_u32 s2, s78, 0x1e742300
	s_addc_u32 s3, s79, 0
	v_writelane_b32 v253, s2, 49
	s_nop 1
	v_writelane_b32 v253, s3, 50
	s_add_u32 s2, s78, 0x1e744400
	s_addc_u32 s3, s79, 0
	v_writelane_b32 v253, s2, 51
	s_nop 1
	v_writelane_b32 v253, s3, 52
	s_add_u32 s2, s78, 0x1e744500
	v_writelane_b32 v253, s78, 53
	s_addc_u32 s3, s79, 0
	s_abs_i32 s4, s71
	v_writelane_b32 v253, s79, 54
	v_writelane_b32 v253, s2, 55
	v_cvt_f32_u32_e32 v1, s4
	s_lshl_b32 s0, s0, 1
	v_writelane_b32 v253, s3, 56
	s_abs_i32 s3, s72
	v_cvt_f32_u32_e32 v0, s3
	v_rcp_iflag_f32_e32 v1, v1
	s_mul_i32 s2, s73, s72
	s_mul_i32 s2, s2, s56
	v_rcp_iflag_f32_e32 v0, v0
	v_writelane_b32 v253, s2, 57
	v_writelane_b32 v253, s3, 58
	s_sub_i32 s2, 0, s3
	v_mul_f32_e32 v0, 0x4f7ffffe, v0
	v_cvt_u32_f32_e32 v0, v0
	s_ashr_i32 s77, s76, 31
	s_add_i32 s56, s55, 0xffffff85
	s_add_i32 s57, 0, 0x23e00
	v_readfirstlane_b32 s3, v0
	v_mul_f32_e32 v0, 0x4f7ffffe, v1
	v_cvt_u32_f32_e32 v0, v0
	s_mul_i32 s2, s2, s3
	s_mul_hi_u32 s2, s3, s2
	s_add_i32 s2, s3, s2
	v_writelane_b32 v253, s2, 59
	s_sub_i32 s2, 0, s4
	v_readfirstlane_b32 s3, v0
	s_mul_i32 s2, s2, s3
	s_mul_hi_u32 s2, s3, s2
	v_writelane_b32 v253, s4, 60
	s_add_i32 s2, s3, s2
	v_writelane_b32 v253, s2, 61
	s_mul_hi_i32 s3, s76, 0x300
	s_mul_i32 s2, s76, 0x300
	v_writelane_b32 v253, s2, 62
	v_mbcnt_lo_u32_b32 v0, -1, 0
	v_mbcnt_hi_u32_b32 v0, -1, v0
	v_writelane_b32 v253, s3, 63
	s_mul_hi_i32 s3, s76, 0x60
	s_mul_i32 s2, s76, 0x60
	v_writelane_b32 v254, s2, 0
	s_add_i32 s69, s61, 0x4000
	s_movk_i32 s73, 0x300
	v_writelane_b32 v254, s3, 1
	s_mul_hi_i32 s3, s76, 0x1400
	s_mul_i32 s2, s76, 0x1400
	v_writelane_b32 v254, s2, 2
	v_add_u32_e32 v246, s6, v0
	s_add_i32 s82, s33, 0x2000
	v_writelane_b32 v254, s3, 3
	v_writelane_b32 v254, s6, 4
	v_writelane_b32 v254, s5, 5
	s_add_i32 s2, s5, s76
	v_writelane_b32 v254, s2, 6
	s_add_i32 s2, s61, 0x8000
	v_writelane_b32 v254, s2, 7
	s_add_i32 s2, s33, 0x3000
	v_writelane_b32 v254, s2, 8
	s_add_i32 s2, s33, 0x1000
	v_writelane_b32 v254, s2, 9
	s_add_i32 s2, 0, 0x23e20
	v_writelane_b32 v254, s2, 10
	s_add_i32 s2, 0, 0x23e24
	v_writelane_b32 v254, s2, 11
	v_writelane_b32 v254, s0, 12
	s_mov_b32 s2, s72
	s_add_i32 s83, s33, 0x6000
	v_writelane_b32 v254, s1, 13
	s_lshl_b32 s0, s1, 1
	v_writelane_b32 v254, s0, 14
	s_mov_b32 s6, 0
	s_mov_b64 s[78:79], 0x80
	v_writelane_b32 v254, s1, 15
	s_lshl_b64 s[0:1], s[76:77], 8
	v_writelane_b32 v254, s0, 16
	s_nop 1
	v_writelane_b32 v254, s1, 17
	s_mov_b32 s0, s76
	v_writelane_b32 v254, s0, 18
	s_nop 1
	v_writelane_b32 v254, s1, 19
	s_lshl_b64 s[0:1], s[76:77], 9
	v_writelane_b32 v254, s0, 20
	s_mov_b64 s[76:77], 0x540
	s_nop 0
	v_writelane_b32 v254, s1, 21
	v_writelane_b32 v254, s2, 22
	s_mov_b64 s[0:1], 0x740
	s_nop 0
	v_writelane_b32 v254, s3, 23
	v_writelane_b32 v254, s52, 24
	s_nop 1
	v_writelane_b32 v254, s53, 25
	v_writelane_b32 v254, s55, 26
	v_writelane_b32 v254, s58, 27
	v_writelane_b32 v254, s59, 28
	v_writelane_b32 v254, s60, 29
	v_writelane_b32 v254, s61, 30
	v_writelane_b32 v254, s62, 31
	v_writelane_b32 v254, s63, 32
	v_writelane_b32 v254, s64, 33
	v_writelane_b32 v254, s66, 34
	s_nop 1
	v_writelane_b32 v254, s67, 35
	v_writelane_b32 v254, s74, 36
	v_writelane_b32 v254, s86, 37
	s_nop 1
	v_writelane_b32 v254, s87, 38
	v_writelane_b32 v254, s88, 39
	v_writelane_b32 v254, s56, 40
	v_writelane_b32 v254, s57, 41
	v_writelane_b32 v254, s69, 42
	s_branch .LBB0_651

; __device__ __forceinline__ void xcd_barrier(const XcdBarrier& b) {
;     asm volatile("s_waitcnt vmcnt(0)" ::: "memory");
;     __syncthreads();
;     if (threadIdx.x == 0) {
;         unsigned* bar = b.bar;
;         __builtin_amdgcn_s_waitcnt(0);
;         unsigned nloc = b.st[0], nx = b.st[1];
;         if (nloc == 0u) { xcd_barrier_complete(bar, b.x, nloc, nx); b.st[0] = nloc; b.st[1] = nx; }
.LBB0_2979:
	v_readlane_b32 s6, v255, 61
	s_cmp_lg_u32 s6, 0
	s_cbranch_scc1 .Lxl_decided
	v_readlane_b32 s6, v254, 53
	s_cmp_lt_u32 s6, 2
	s_cbranch_scc1 .Lxl_decided
	v_readlane_b32 s6, v253, 2
	v_readlane_b32 s7, v253, 3
	s_nop 4
	global_load_dword v1, v215, s[6:7] offset:544 sc1
	s_waitcnt vmcnt(0)
	v_readfirstlane_b32 s6, v1
	s_cmp_eq_u32 s6, 0
	s_cselect_b32 s6, 1, 2
	s_nop 0
	v_writelane_b32 v255, s6, 61

; __device__ __forceinline__ unsigned xb_ld(unsigned* p)              { return __hip_atomic_load(p, __ATOMIC_RELAXED, __HIP_MEMORY_SCOPE_AGENT); }
; __device__ __forceinline__ unsigned xb_add(unsigned* p, unsigned v) { return __hip_atomic_fetch_add(p, v, __ATOMIC_RELAXED, __HIP_MEMORY_SCOPE_AGENT); }
; #define XB_SPIN(cond, bar) do { unsigned _sp = 0; while (cond) { __builtin_amdgcn_s_sleep(1); \
;     if ((++_sp & 255u) == 0u) { if (xb_ld(&(bar)[XB_TMO])) break; if (_sp > XB_SPIN_CAP) { atomicAdd(&(bar)[XB_TMO], 1u); break; } } } } while (0)
; __device__ __forceinline__ void xcd_barrier(const XcdBarrier& b) {
;     ...
;         const unsigned old = xb_add(&bar[XB_XSUB(b.x)], 1u);
;         const unsigned gen = old / nloc;
;         if (old + 1u == (gen + 1u) * nloc) {
;             __builtin_amdgcn_fence(__ATOMIC_RELEASE, "agent");
;             asm volatile("s_waitcnt vmcnt(0)" ::: "memory");
;             const unsigned og = xb_add(&bar[XB_TOP], 1u);
;             const unsigned tg = og / nx;
;             if (og + 1u == (tg + 1u) * nx) xb_add(&bar[XB_TOPGEN], 1u);
;             else XB_SPIN(xb_ld(&bar[XB_TOPGEN]) == tg, bar);
.LBB0_2996:
	v_readlane_b32 s6, v255, 61
	s_cmp_lg_u32 s6, 1
	s_cbranch_scc1 .Lxl_full
	v_readlane_b32 s6, v254, 52
	v_readlane_b32 s7, v254, 53
	s_cmp_eq_u32 s6, 1
	s_cbranch_scc1 .Lxl_go
	s_cmp_eq_u32 s6, 10
	s_cbranch_scc1 .Lxl_go
	s_cmp_eq_u32 s6, 12
	s_cbranch_scc1 .Lxl_go
	s_cmp_lg_u32 s6, 13
	s_cbranch_scc1 .Lxl_full
	s_cmp_lg_u32 s7, 13
	s_cbranch_scc1 .Lxl_full
.Lxl_go:
	s_waitcnt lgkmcnt(0)
	s_branch .Lxl_local
.Lxl_full:
	s_mov_b64 s[6:7], exec
	buffer_wbl2 sc1
	s_waitcnt lgkmcnt(0)
	s_waitcnt vmcnt(0)
	v_mbcnt_lo_u32_b32 v1, s6, 0
	v_mbcnt_hi_u32_b32 v1, s7, v1
	v_cmp_eq_u32_e32 vcc, 0, v1
	s_and_saveexec_b64 s[8:9], vcc
	s_cbranch_execz .LBB0_2998
	s_bcnt1_i32_b64 s6, s[6:7]
	v_mov_b32_e32 v2, s6
	v_readlane_b32 s6, v253, 51
	v_readlane_b32 s7, v253, 52
	s_nop 4
	global_atomic_add v2, v215, v2, s[6:7] sc0

; __device__ __forceinline__ unsigned xb_add(unsigned* p, unsigned v) { return __hip_atomic_fetch_add(p, v, __ATOMIC_RELAXED, __HIP_MEMORY_SCOPE_AGENT); }
; __device__ __forceinline__ void xcd_barrier(const XcdBarrier& b) {
;     ...
;             __builtin_amdgcn_fence(__ATOMIC_ACQUIRE, "agent");
;             xb_add(&bar[XB_XGEN(b.x)], 1u);
;             asm volatile("s_waitcnt vmcnt(0)" ::: "memory");
.Lxl_local:
	s_mov_b64 s[6:7], exec
	v_mbcnt_lo_u32_b32 v0, s6, 0
	v_mbcnt_hi_u32_b32 v0, s7, v0
	v_cmp_eq_u32_e32 vcc, 0, v0
	s_waitcnt vmcnt(0)
	buffer_inv sc1
	s_and_saveexec_b64 s[8:9], vcc
	s_cbranch_execnz .LBB0_3014
	s_getpc_b64 s[98:99]
